# two redundant lgkmcnt(15) waits per P.V block removed
# speedup vs baseline: 1.0017x; 1.0017x over previous
; #define LAS __attribute__((address_space(3)))
; #define MFMA32(a, b, c) __builtin_amdgcn_mfma_f32_32x32x16_bf16((a), (b), (c), 0, 0, 0)
; #define AT_ISSUE_V(jn) do { const int jc_ = (jn) < ntm1 ? (jn) : ntm1; const size_t vo_ = (size_t)jc_ * 16384; vs0 = *(const u32x4*)(bV0 + vo_ + voff); vs1 = *(const u32x4*)(bV1 + vo_ + voff); } while (0)
; #define AT_WRITE_K(jn) do { LAS unsigned char* n_ = lds + ((jn) & 1) * AT_KST; *(LAS u32x4*)(n_ + dK1) = ks0; *(LAS u32x4*)(n_ + dK2) = ks1; } while (0)
; __device__ __forceinline__ void at_pv_half(const LAS unsigned char* vp, const bf16x8 (&pf)[4], f32x16 (&O)[4], f32x16& L) {
;     bf16x8 va[8], vb[8];
; #pragma unroll
;     for (int e = 0; e < 2; ++e)
; #pragma unroll
;         for (int ks = 0; ks < 4; ++ks) va[e * 4 + ks] = *(const LAS bf16x8*)(vp + e * 32 * AT_ROWB + 32 * ks);
; #pragma unroll
;     for (int e = 0; e < 2; ++e)
; #pragma unroll
;         for (int ks = 0; ks < 4; ++ks) vb[e * 4 + ks] = *(const LAS bf16x8*)(vp + (2 + e) * 32 * AT_ROWB + 32 * ks);
;     const short one = (short)0x3F80; const bf16x8 ones = {one, one, one, one, one, one, one, one};
;     __builtin_amdgcn_sched_barrier(0);
;     __builtin_amdgcn_s_setprio(1);
; #pragma unroll
;     for (int ks = 0; ks < 4; ++ks) L = MFMA32(ones, pf[ks], L);
;     __builtin_amdgcn_sched_barrier(0);
; #pragma unroll
;     for (int ks = 0; ks < 4; ++ks) { O[0] = MFMA32(va[ks], pf[ks], O[0]); O[1] = MFMA32(va[4 + ks], pf[ks], O[1]); }
; #pragma unroll
;     for (int ks = 0; ks < 4; ++ks) { O[2] = MFMA32(vb[ks], pf[ks], O[2]); O[3] = MFMA32(vb[4 + ks], pf[ks], O[3]); }
;     __builtin_amdgcn_s_setprio(0);
; }
; __device__ __forceinline__ void attn_item(LAS unsigned char* lds, const bf16_t* Q, const bf16_t* Kb, const bf16_t* VT, bf16_t* aout, const float* subg, float lam, float omli, float kbound, int head, int qb) {
;     ...
;             AT_ISSUE_V(j + 1);
;             if (j > 0 && kbase - 64 <= qmax) at_pv_half(pst + vfo, pf, O, L);
;             AT_WRITE_K(j + 1);
.Lmy_top1:
	s_cbranch_vccnz .LBB0_297
	ds_read_b128 v[96:99], v184 offset:36864
	ds_read_b128 v[154:157], v184 offset:41472
	ds_read_b128 v[170:173], v184 offset:46080
	ds_read_b128 v[236:239], v184 offset:50688
	ds_read_b128 v[100:103], v184 offset:36896
	ds_read_b128 v[158:161], v184 offset:41504
	ds_read_b128 v[174:177], v184 offset:46112
	ds_read_b128 v[240:243], v184 offset:50720
	ds_read_b128 v[104:107], v184 offset:36928
	ds_read_b128 v[162:165], v184 offset:41536
	ds_read_b128 v[178:181], v184 offset:46144
	ds_read_b128 v[244:247], v184 offset:50752
	ds_read_b128 v[108:111], v184 offset:36960
	ds_read_b128 v[166:169], v184 offset:41568
	ds_read_b128 v[232:235], v184 offset:46176
	ds_read_b128 v[248:251], v184 offset:50784
	s_setprio 1
	v_mfma_f32_16x16x32_bf16 v[64:67], v[76:79], v[80:83], v[64:67]
	v_mfma_f32_16x16x32_bf16 v[64:67], v[76:79], v[88:91], v[64:67]
	v_mfma_f32_16x16x32_bf16 v[64:67], v[76:79], v[84:87], v[64:67]
	v_mfma_f32_16x16x32_bf16 v[64:67], v[76:79], v[92:95], v[64:67]
	v_add_u32_e32 v185, s56, v212
	s_waitcnt vmcnt(3)
	ds_write_b128 v185, v[142:145]
	s_waitcnt vmcnt(2)
	ds_write_b128 v185, v[138:141] offset:9216
	s_waitcnt lgkmcnt(15)
	v_mfma_f32_32x32x16_bf16 v[48:63], v[96:99], v[80:83], v[48:63]
	v_mfma_f32_32x32x16_bf16 v[32:47], v[154:157], v[80:83], v[32:47]
	v_mfma_f32_32x32x16_bf16 v[16:31], v[170:173], v[80:83], v[16:31]
	s_waitcnt lgkmcnt(14)
	v_mfma_f32_32x32x16_bf16 v[0:15], v[236:239], v[80:83], v[0:15]
	s_waitcnt lgkmcnt(13)
	v_mfma_f32_32x32x16_bf16 v[48:63], v[100:103], v[88:91], v[48:63]
	s_waitcnt lgkmcnt(12)
	v_mfma_f32_32x32x16_bf16 v[32:47], v[158:161], v[88:91], v[32:47]
	s_waitcnt lgkmcnt(11)
	v_mfma_f32_32x32x16_bf16 v[16:31], v[174:177], v[88:91], v[16:31]
	s_waitcnt lgkmcnt(10)
	v_mfma_f32_32x32x16_bf16 v[0:15], v[240:243], v[88:91], v[0:15]
	s_waitcnt lgkmcnt(9)
	v_mfma_f32_32x32x16_bf16 v[48:63], v[104:107], v[84:87], v[48:63]
	s_waitcnt lgkmcnt(8)
	v_mfma_f32_32x32x16_bf16 v[32:47], v[162:165], v[84:87], v[32:47]
	s_waitcnt lgkmcnt(7)
	v_mfma_f32_32x32x16_bf16 v[16:31], v[178:181], v[84:87], v[16:31]
	s_waitcnt lgkmcnt(6)
	v_mfma_f32_32x32x16_bf16 v[0:15], v[244:247], v[84:87], v[0:15]
	s_waitcnt lgkmcnt(5)
	v_mfma_f32_32x32x16_bf16 v[48:63], v[108:111], v[92:95], v[48:63]
	s_waitcnt lgkmcnt(4)
	v_mfma_f32_32x32x16_bf16 v[32:47], v[166:169], v[92:95], v[32:47]
	s_waitcnt lgkmcnt(3)
	v_mfma_f32_32x32x16_bf16 v[16:31], v[232:235], v[92:95], v[16:31]
	s_waitcnt lgkmcnt(2)
	v_mfma_f32_32x32x16_bf16 v[0:15], v[248:251], v[92:95], v[0:15]
	s_setprio 0
	s_branch .Lmy_wj1

; #define LAS __attribute__((address_space(3)))
; #define MFMA32(a, b, c) __builtin_amdgcn_mfma_f32_32x32x16_bf16((a), (b), (c), 0, 0, 0)
; #define AT_ISSUE_K(jn) do { const int jc_ = (jn) < ntm1 ? (jn) : ntm1; const size_t ko_ = (size_t)jc_ * 8192; ks0 = *(const u32x4*)(bK1 + ko_ + koff); ks1 = *(const u32x4*)(bK2 + ko_ + koff); } while (0)
; #define AT_WRITE_K(jn) do { LAS unsigned char* n_ = lds + ((jn) & 1) * AT_KST; *(LAS u32x4*)(n_ + dK1) = ks0; *(LAS u32x4*)(n_ + dK2) = ks1; } while (0)
; #define AT_WRITE_V(jn) do { LAS unsigned char* n_ = lds + ((jn) & 1) * AT_KST; *(LAS u32x4*)(n_ + dV0) = vs0; *(LAS u32x4*)(n_ + dV1) = vs1; } while (0)
; __device__ __forceinline__ void at_pv_half(const LAS unsigned char* vp, const bf16x8 (&pf)[4], f32x16 (&O)[4], f32x16& L) {
;     bf16x8 va[8], vb[8];
; #pragma unroll
;     for (int e = 0; e < 2; ++e)
; #pragma unroll
;         for (int ks = 0; ks < 4; ++ks) va[e * 4 + ks] = *(const LAS bf16x8*)(vp + e * 32 * AT_ROWB + 32 * ks);
; #pragma unroll
;     for (int e = 0; e < 2; ++e)
; #pragma unroll
;         for (int ks = 0; ks < 4; ++ks) vb[e * 4 + ks] = *(const LAS bf16x8*)(vp + (2 + e) * 32 * AT_ROWB + 32 * ks);
;     const short one = (short)0x3F80; const bf16x8 ones = {one, one, one, one, one, one, one, one};
;     __builtin_amdgcn_sched_barrier(0);
;     __builtin_amdgcn_s_setprio(1);
; #pragma unroll
;     for (int ks = 0; ks < 4; ++ks) L = MFMA32(ones, pf[ks], L);
;     __builtin_amdgcn_sched_barrier(0);
; #pragma unroll
;     for (int ks = 0; ks < 4; ++ks) { O[0] = MFMA32(va[ks], pf[ks], O[0]); O[1] = MFMA32(va[4 + ks], pf[ks], O[1]); }
; #pragma unroll
;     for (int ks = 0; ks < 4; ++ks) { O[2] = MFMA32(vb[ks], pf[ks], O[2]); O[3] = MFMA32(vb[4 + ks], pf[ks], O[3]); }
;     __builtin_amdgcn_s_setprio(0);
; }
; __device__ __forceinline__ void attn_item(LAS unsigned char* lds, const bf16_t* Q, const bf16_t* Kb, const bf16_t* VT, bf16_t* aout, const float* subg, float lam, float omli, float kbound, int head, int qb) {
;     ...
;             __builtin_amdgcn_s_setprio(3);
;             AT_WRITE_K(j + 1);
;             __syncthreads();
;             __builtin_amdgcn_s_setprio(0);
;             AT_ISSUE_K(j + 2);
;             if (act) at_pv_half(stg + vfo, pf, O, L);
;             AT_WRITE_V(j + 1);
.LBB0_320:
	s_setprio 3
	s_bitcmp1_b32 s56, 0
	s_cselect_b32 s55, 0x4800, 0
	s_waitcnt lgkmcnt(7)
	v_add_u32_e32 v96, s55, v213
	s_waitcnt vmcnt(3)
	ds_write_b128 v96, v[130:133]
	s_waitcnt vmcnt(2)
	ds_write_b128 v96, v[134:137] offset:9216
	s_waitcnt lgkmcnt(0)
	s_add_i32 s53, s53, 2
	s_min_i32 s58, s53, s41
	s_lshl_b64 s[60:61], s[58:59], 13
	v_lshl_add_u64 v[98:99], v[204:205], 0, s[60:61]
	v_lshl_add_u64 v[100:101], v[206:207], 0, s[60:61]
	global_load_dwordx4 v[130:133], v[98:99], off
	global_load_dwordx4 v[134:137], v[100:101], off
	s_andn2_b64 vcc, exec, s[0:1]
	v_add_u32_e32 v97, s54, v228
	s_barrier
	s_setprio 0
	s_cbranch_vccnz .LBB0_322
	ds_read_b128 v[98:101], v97 offset:36864
	ds_read_b128 v[150:153], v97 offset:41472
	ds_read_b128 v[166:169], v97 offset:46080
	ds_read_b128 v[234:237], v97 offset:50688
	ds_read_b128 v[102:105], v97 offset:36896
	ds_read_b128 v[154:157], v97 offset:41504
	ds_read_b128 v[170:173], v97 offset:46112
	ds_read_b128 v[238:241], v97 offset:50720
	ds_read_b128 v[106:109], v97 offset:36928
	ds_read_b128 v[158:161], v97 offset:41536
	ds_read_b128 v[176:179], v97 offset:46144
	ds_read_b128 v[242:245], v97 offset:50752
	ds_read_b128 v[146:149], v97 offset:36960
	ds_read_b128 v[162:165], v97 offset:41568
	ds_read_b128 v[230:233], v97 offset:46176
	ds_read_b128 v[246:249], v97 offset:50784
	s_setprio 1
	v_mfma_f32_16x16x32_bf16 v[64:67], v[76:79], v[80:83], v[64:67]
	v_mfma_f32_16x16x32_bf16 v[64:67], v[76:79], v[88:91], v[64:67]
	v_mfma_f32_16x16x32_bf16 v[64:67], v[76:79], v[84:87], v[64:67]
	v_mfma_f32_16x16x32_bf16 v[64:67], v[76:79], v[92:95], v[64:67]
	s_waitcnt vmcnt(3)
	ds_write_b128 v96, v[138:141] offset:36864
	s_waitcnt vmcnt(2)
	ds_write_b128 v96, v[142:145] offset:46080
	s_waitcnt lgkmcnt(15)
	v_mfma_f32_32x32x16_bf16 v[48:63], v[98:101], v[80:83], v[48:63]
	v_mfma_f32_32x32x16_bf16 v[32:47], v[150:153], v[80:83], v[32:47]
	v_mfma_f32_32x32x16_bf16 v[16:31], v[166:169], v[80:83], v[16:31]
	s_waitcnt lgkmcnt(14)
	v_mfma_f32_32x32x16_bf16 v[0:15], v[234:237], v[80:83], v[0:15]
	s_waitcnt lgkmcnt(13)
	v_mfma_f32_32x32x16_bf16 v[48:63], v[102:105], v[88:91], v[48:63]
	s_waitcnt lgkmcnt(12)
	v_mfma_f32_32x32x16_bf16 v[32:47], v[154:157], v[88:91], v[32:47]
	s_waitcnt lgkmcnt(11)
	v_mfma_f32_32x32x16_bf16 v[16:31], v[170:173], v[88:91], v[16:31]
	s_waitcnt lgkmcnt(10)
	v_mfma_f32_32x32x16_bf16 v[0:15], v[238:241], v[88:91], v[0:15]
	s_waitcnt lgkmcnt(9)
	v_mfma_f32_32x32x16_bf16 v[48:63], v[106:109], v[84:87], v[48:63]
	s_waitcnt lgkmcnt(8)
	v_mfma_f32_32x32x16_bf16 v[32:47], v[158:161], v[84:87], v[32:47]
	s_waitcnt lgkmcnt(7)
	v_mfma_f32_32x32x16_bf16 v[16:31], v[176:179], v[84:87], v[16:31]
	s_waitcnt lgkmcnt(6)
	v_mfma_f32_32x32x16_bf16 v[0:15], v[242:245], v[84:87], v[0:15]
	s_waitcnt lgkmcnt(5)
	v_mfma_f32_32x32x16_bf16 v[48:63], v[146:149], v[92:95], v[48:63]
	s_waitcnt lgkmcnt(4)
	v_mfma_f32_32x32x16_bf16 v[32:47], v[162:165], v[92:95], v[32:47]
	s_waitcnt lgkmcnt(3)
	v_mfma_f32_32x32x16_bf16 v[16:31], v[230:233], v[92:95], v[16:31]
	s_waitcnt lgkmcnt(2)
	v_mfma_f32_32x32x16_bf16 v[0:15], v[246:249], v[92:95], v[0:15]
	s_setprio 0
	s_branch .Lmy_wj3

; #define LAS __attribute__((address_space(3)))
; #define MFMA32(a, b, c) __builtin_amdgcn_mfma_f32_32x32x16_bf16((a), (b), (c), 0, 0, 0)
; #define AT_ISSUE_V(jn) do { const int jc_ = (jn) < ntm1 ? (jn) : ntm1; const size_t vo_ = (size_t)jc_ * 16384; vs0 = *(const u32x4*)(bV0 + vo_ + voff); vs1 = *(const u32x4*)(bV1 + vo_ + voff); } while (0)
; #define AT_WRITE_K(jn) do { LAS unsigned char* n_ = lds + ((jn) & 1) * AT_KST; *(LAS u32x4*)(n_ + dK1) = ks0; *(LAS u32x4*)(n_ + dK2) = ks1; } while (0)
; __device__ __forceinline__ void at_pv_half(const LAS unsigned char* vp, const bf16x8 (&pf)[4], f32x16 (&O)[4], f32x16& L) {
;     bf16x8 va[8], vb[8];
; #pragma unroll
;     for (int e = 0; e < 2; ++e)
; #pragma unroll
;         for (int ks = 0; ks < 4; ++ks) va[e * 4 + ks] = *(const LAS bf16x8*)(vp + e * 32 * AT_ROWB + 32 * ks);
; #pragma unroll
;     for (int e = 0; e < 2; ++e)
; #pragma unroll
;         for (int ks = 0; ks < 4; ++ks) vb[e * 4 + ks] = *(const LAS bf16x8*)(vp + (2 + e) * 32 * AT_ROWB + 32 * ks);
;     const short one = (short)0x3F80; const bf16x8 ones = {one, one, one, one, one, one, one, one};
;     __builtin_amdgcn_sched_barrier(0);
;     __builtin_amdgcn_s_setprio(1);
; #pragma unroll
;     for (int ks = 0; ks < 4; ++ks) L = MFMA32(ones, pf[ks], L);
;     __builtin_amdgcn_sched_barrier(0);
; #pragma unroll
;     for (int ks = 0; ks < 4; ++ks) { O[0] = MFMA32(va[ks], pf[ks], O[0]); O[1] = MFMA32(va[4 + ks], pf[ks], O[1]); }
; #pragma unroll
;     for (int ks = 0; ks < 4; ++ks) { O[2] = MFMA32(vb[ks], pf[ks], O[2]); O[3] = MFMA32(vb[4 + ks], pf[ks], O[3]); }
;     __builtin_amdgcn_s_setprio(0);
; }
; __device__ __forceinline__ void attn_item(LAS unsigned char* lds, const bf16_t* Q, const bf16_t* Kb, const bf16_t* VT, bf16_t* aout, const float* subg, float lam, float omli, float kbound, int head, int qb) {
;     ...
;             AT_ISSUE_V(j + 1);
;             if (j > 0 && kbase - 64 <= qmax) at_pv_half(pst + vfo, pf, O, L);
;             AT_WRITE_K(j + 1);
.Lmy_top4:
	s_cbranch_vccnz .LBB0_335
	ds_read_b128 v[96:99], v244 offset:36864
	ds_read_b128 v[154:157], v244 offset:41472
	ds_read_b128 v[170:173], v244 offset:46080
	ds_read_b128 v[232:235], v244 offset:50688
	ds_read_b128 v[100:103], v244 offset:36896
	ds_read_b128 v[158:161], v244 offset:41504
	ds_read_b128 v[174:177], v244 offset:46112
	ds_read_b128 v[236:239], v244 offset:50720
	ds_read_b128 v[104:107], v244 offset:36928
	ds_read_b128 v[162:165], v244 offset:41536
	ds_read_b128 v[178:181], v244 offset:46144
	ds_read_b128 v[240:243], v244 offset:50752
	ds_read_b128 v[108:111], v244 offset:36960
	ds_read_b128 v[166:169], v244 offset:41568
	ds_read_b128 v[184:187], v244 offset:46176
	ds_read_b128 v[244:247], v244 offset:50784
	s_setprio 1
	v_mfma_f32_16x16x32_bf16 v[64:67], v[76:79], v[80:83], v[64:67]
	v_mfma_f32_16x16x32_bf16 v[64:67], v[76:79], v[88:91], v[64:67]
	v_mfma_f32_16x16x32_bf16 v[64:67], v[76:79], v[84:87], v[64:67]
	v_mfma_f32_16x16x32_bf16 v[64:67], v[76:79], v[92:95], v[64:67]
	v_add_u32_e32 v249, s40, v212
	s_waitcnt vmcnt(3)
	ds_write_b128 v249, v[142:145]
	s_waitcnt vmcnt(2)
	ds_write_b128 v249, v[138:141] offset:9216
	s_waitcnt lgkmcnt(15)
	v_mfma_f32_32x32x16_bf16 v[48:63], v[96:99], v[80:83], v[48:63]
	v_mfma_f32_32x32x16_bf16 v[32:47], v[154:157], v[80:83], v[32:47]
	v_mfma_f32_32x32x16_bf16 v[16:31], v[170:173], v[80:83], v[16:31]
	s_waitcnt lgkmcnt(14)
	v_mfma_f32_32x32x16_bf16 v[0:15], v[232:235], v[80:83], v[0:15]
	s_waitcnt lgkmcnt(13)
	v_mfma_f32_32x32x16_bf16 v[48:63], v[100:103], v[88:91], v[48:63]
	s_waitcnt lgkmcnt(12)
	v_mfma_f32_32x32x16_bf16 v[32:47], v[158:161], v[88:91], v[32:47]
	s_waitcnt lgkmcnt(11)
	v_mfma_f32_32x32x16_bf16 v[16:31], v[174:177], v[88:91], v[16:31]
	s_waitcnt lgkmcnt(10)
	v_mfma_f32_32x32x16_bf16 v[0:15], v[236:239], v[88:91], v[0:15]
	s_waitcnt lgkmcnt(9)
	v_mfma_f32_32x32x16_bf16 v[48:63], v[104:107], v[84:87], v[48:63]
	s_waitcnt lgkmcnt(8)
	v_mfma_f32_32x32x16_bf16 v[32:47], v[162:165], v[84:87], v[32:47]
	s_waitcnt lgkmcnt(7)
	v_mfma_f32_32x32x16_bf16 v[16:31], v[178:181], v[84:87], v[16:31]
	s_waitcnt lgkmcnt(6)
	v_mfma_f32_32x32x16_bf16 v[0:15], v[240:243], v[84:87], v[0:15]
	s_waitcnt lgkmcnt(5)
	v_mfma_f32_32x32x16_bf16 v[48:63], v[108:111], v[92:95], v[48:63]
	s_waitcnt lgkmcnt(4)
	v_mfma_f32_32x32x16_bf16 v[32:47], v[166:169], v[92:95], v[32:47]
	s_waitcnt lgkmcnt(3)
	v_mfma_f32_32x32x16_bf16 v[16:31], v[184:187], v[92:95], v[16:31]
	s_waitcnt lgkmcnt(2)
	v_mfma_f32_32x32x16_bf16 v[0:15], v[244:247], v[92:95], v[0:15]
	s_setprio 0
	s_branch .Lmy_wj4

; #define LAS __attribute__((address_space(3)))
; #define MFMA32(a, b, c) __builtin_amdgcn_mfma_f32_32x32x16_bf16((a), (b), (c), 0, 0, 0)
; #define AT_ISSUE_K(jn) do { const int jc_ = (jn) < ntm1 ? (jn) : ntm1; const size_t ko_ = (size_t)jc_ * 8192; ks0 = *(const u32x4*)(bK1 + ko_ + koff); ks1 = *(const u32x4*)(bK2 + ko_ + koff); } while (0)
; #define AT_WRITE_K(jn) do { LAS unsigned char* n_ = lds + ((jn) & 1) * AT_KST; *(LAS u32x4*)(n_ + dK1) = ks0; *(LAS u32x4*)(n_ + dK2) = ks1; } while (0)
; #define AT_WRITE_V(jn) do { LAS unsigned char* n_ = lds + ((jn) & 1) * AT_KST; *(LAS u32x4*)(n_ + dV0) = vs0; *(LAS u32x4*)(n_ + dV1) = vs1; } while (0)
; __device__ __forceinline__ void at_pv_half(const LAS unsigned char* vp, const bf16x8 (&pf)[4], f32x16 (&O)[4], f32x16& L) {
;     bf16x8 va[8], vb[8];
; #pragma unroll
;     for (int e = 0; e < 2; ++e)
; #pragma unroll
;         for (int ks = 0; ks < 4; ++ks) va[e * 4 + ks] = *(const LAS bf16x8*)(vp + e * 32 * AT_ROWB + 32 * ks);
; #pragma unroll
;     for (int e = 0; e < 2; ++e)
; #pragma unroll
;         for (int ks = 0; ks < 4; ++ks) vb[e * 4 + ks] = *(const LAS bf16x8*)(vp + (2 + e) * 32 * AT_ROWB + 32 * ks);
;     const short one = (short)0x3F80; const bf16x8 ones = {one, one, one, one, one, one, one, one};
;     __builtin_amdgcn_sched_barrier(0);
;     __builtin_amdgcn_s_setprio(1);
; #pragma unroll
;     for (int ks = 0; ks < 4; ++ks) L = MFMA32(ones, pf[ks], L);
;     __builtin_amdgcn_sched_barrier(0);
; #pragma unroll
;     for (int ks = 0; ks < 4; ++ks) { O[0] = MFMA32(va[ks], pf[ks], O[0]); O[1] = MFMA32(va[4 + ks], pf[ks], O[1]); }
; #pragma unroll
;     for (int ks = 0; ks < 4; ++ks) { O[2] = MFMA32(vb[ks], pf[ks], O[2]); O[3] = MFMA32(vb[4 + ks], pf[ks], O[3]); }
;     __builtin_amdgcn_s_setprio(0);
; }
; __device__ __forceinline__ void attn_item(LAS unsigned char* lds, const bf16_t* Q, const bf16_t* Kb, const bf16_t* VT, bf16_t* aout, const float* subg, float lam, float omli, float kbound, int head, int qb) {
;     ...
;             __builtin_amdgcn_s_setprio(3);
;             AT_WRITE_K(j + 1);
;             __syncthreads();
;             __builtin_amdgcn_s_setprio(0);
;             AT_ISSUE_K(j + 2);
;             if (act) at_pv_half(stg + vfo, pf, O, L);
;             AT_WRITE_V(j + 1);
.LBB0_358:
	s_setprio 3
	s_bitcmp1_b32 s39, 0
	s_cselect_b32 s41, 0x4800, 0
	s_waitcnt lgkmcnt(7)
	v_add_u32_e32 v96, s41, v213
	s_waitcnt vmcnt(3)
	ds_write_b128 v96, v[130:133]
	s_waitcnt vmcnt(2)
	ds_write_b128 v96, v[134:137] offset:9216
	s_waitcnt lgkmcnt(0)
	s_add_i32 s38, s38, 2
	s_min_i32 s58, s38, s22
	s_lshl_b64 s[42:43], s[58:59], 13
	v_lshl_add_u64 v[98:99], v[204:205], 0, s[42:43]
	v_lshl_add_u64 v[100:101], v[206:207], 0, s[42:43]
	global_load_dwordx4 v[130:133], v[98:99], off
	global_load_dwordx4 v[134:137], v[100:101], off
	s_andn2_b64 vcc, exec, s[0:1]
	v_add_u32_e32 v97, s40, v228
	s_barrier
	s_setprio 0
	s_cbranch_vccnz .LBB0_360
	ds_read_b128 v[98:101], v97 offset:36864
	ds_read_b128 v[150:153], v97 offset:41472
	ds_read_b128 v[166:169], v97 offset:46080
	ds_read_b128 v[230:233], v97 offset:50688
	ds_read_b128 v[102:105], v97 offset:36896
	ds_read_b128 v[154:157], v97 offset:41504
	ds_read_b128 v[170:173], v97 offset:46112
	ds_read_b128 v[234:237], v97 offset:50720
	ds_read_b128 v[106:109], v97 offset:36928
	ds_read_b128 v[158:161], v97 offset:41536
	ds_read_b128 v[176:179], v97 offset:46144
	ds_read_b128 v[238:241], v97 offset:50752
	ds_read_b128 v[146:149], v97 offset:36960
	ds_read_b128 v[162:165], v97 offset:41568
	ds_read_b128 v[184:187], v97 offset:46176
	ds_read_b128 v[242:245], v97 offset:50784
	s_setprio 1
	v_mfma_f32_16x16x32_bf16 v[64:67], v[76:79], v[80:83], v[64:67]
	v_mfma_f32_16x16x32_bf16 v[64:67], v[76:79], v[88:91], v[64:67]
	v_mfma_f32_16x16x32_bf16 v[64:67], v[76:79], v[84:87], v[64:67]
	v_mfma_f32_16x16x32_bf16 v[64:67], v[76:79], v[92:95], v[64:67]
	s_waitcnt vmcnt(3)
	ds_write_b128 v96, v[138:141] offset:36864
	s_waitcnt vmcnt(2)
	ds_write_b128 v96, v[142:145] offset:46080
	s_waitcnt lgkmcnt(15)
	v_mfma_f32_32x32x16_bf16 v[48:63], v[98:101], v[80:83], v[48:63]
	v_mfma_f32_32x32x16_bf16 v[32:47], v[150:153], v[80:83], v[32:47]
	v_mfma_f32_32x32x16_bf16 v[16:31], v[166:169], v[80:83], v[16:31]
	s_waitcnt lgkmcnt(14)
	v_mfma_f32_32x32x16_bf16 v[0:15], v[230:233], v[80:83], v[0:15]
	s_waitcnt lgkmcnt(13)
	v_mfma_f32_32x32x16_bf16 v[48:63], v[102:105], v[88:91], v[48:63]
	s_waitcnt lgkmcnt(12)
	v_mfma_f32_32x32x16_bf16 v[32:47], v[154:157], v[88:91], v[32:47]
	s_waitcnt lgkmcnt(11)
	v_mfma_f32_32x32x16_bf16 v[16:31], v[170:173], v[88:91], v[16:31]
	s_waitcnt lgkmcnt(10)
	v_mfma_f32_32x32x16_bf16 v[0:15], v[234:237], v[88:91], v[0:15]
	s_waitcnt lgkmcnt(9)
	v_mfma_f32_32x32x16_bf16 v[48:63], v[106:109], v[84:87], v[48:63]
	s_waitcnt lgkmcnt(8)
	v_mfma_f32_32x32x16_bf16 v[32:47], v[158:161], v[84:87], v[32:47]
	s_waitcnt lgkmcnt(7)
	v_mfma_f32_32x32x16_bf16 v[16:31], v[176:179], v[84:87], v[16:31]
	s_waitcnt lgkmcnt(6)
	v_mfma_f32_32x32x16_bf16 v[0:15], v[238:241], v[84:87], v[0:15]
	s_waitcnt lgkmcnt(5)
	v_mfma_f32_32x32x16_bf16 v[48:63], v[146:149], v[92:95], v[48:63]
	s_waitcnt lgkmcnt(4)
	v_mfma_f32_32x32x16_bf16 v[32:47], v[162:165], v[92:95], v[32:47]
	s_waitcnt lgkmcnt(3)
	v_mfma_f32_32x32x16_bf16 v[16:31], v[184:187], v[92:95], v[16:31]
	s_waitcnt lgkmcnt(2)
	v_mfma_f32_32x32x16_bf16 v[0:15], v[242:245], v[92:95], v[0:15]
	s_setprio 0
	s_branch .Lmy_wj6
